# P2 rel-pos bias table built with one batch of loads instead of 2-3 dependent rounds
# speedup vs baseline: 1.0025x; 1.0025x over previous
; #define LAS __attribute__((address_space(3)))
; __global__ void __launch_bounds__(NWAVES * 64, 2) fwd_megakernel(Args args) {
;     ...
;         LAS float* tbl = (LAS float*)(lds + TBL_OFF);
;         for (int i = tid; i < 8 * 257; i += NWAVES * 64) tbl[i] = (rel_bias[i] - rel_bias[(i / 257) * 257 + 256]) * LOG2E;
;         __syncthreads();
.LBB0_521:
	s_or_b64 exec, exec, s[0:1]
	v_mov_b32_e32 v2, v0
	s_movk_i32 s0, 0x808
	s_waitcnt lgkmcnt(0)
	s_barrier
	s_nop 0
	v_readfirstlane_b32 s13, v2
	v_cmp_gt_i32_e32 vcc, s0, v2
	s_and_saveexec_b64 s[0:1], vcc
	s_cbranch_execz .LBB0_534
	v_mov_b32_e32 v10, 0xff01
	v_add_u32_e32 v3, 0x200, v2
	v_add_u32_e32 v4, 0x400, v2
	v_add_u32_e32 v5, 0x600, v2
	v_add_u32_e32 v6, 0x800, v2
	v_min_u32_e32 v6, 0x807, v6
	v_lshlrev_b32_e32 v11, 2, v2
	v_lshlrev_b32_e32 v12, 2, v3
	v_lshlrev_b32_e32 v13, 2, v4
	v_lshlrev_b32_e32 v14, 2, v5
	v_lshlrev_b32_e32 v15, 2, v6
	global_load_dword v21, v11, s[90:91]
	global_load_dword v22, v12, s[90:91]
	global_load_dword v23, v13, s[90:91]
	global_load_dword v24, v14, s[90:91]
	global_load_dword v25, v15, s[90:91]
	v_mul_u32_u24_e32 v16, v2, v10
	v_lshrrev_b32_e32 v16, 24, v16
	v_lshl_add_u32 v16, v16, 8, v16
	v_lshlrev_b32_e32 v16, 2, v16
	v_mul_u32_u24_e32 v17, v3, v10
	v_lshrrev_b32_e32 v17, 24, v17
	v_lshl_add_u32 v17, v17, 8, v17
	v_lshlrev_b32_e32 v17, 2, v17
	v_mul_u32_u24_e32 v18, v4, v10
	v_lshrrev_b32_e32 v18, 24, v18
	v_lshl_add_u32 v18, v18, 8, v18
	v_lshlrev_b32_e32 v18, 2, v18
	v_mul_u32_u24_e32 v19, v5, v10
	v_lshrrev_b32_e32 v19, 24, v19
	v_lshl_add_u32 v19, v19, 8, v19
	v_lshlrev_b32_e32 v19, 2, v19
	v_mul_u32_u24_e32 v20, v6, v10
	v_lshrrev_b32_e32 v20, 24, v20
	v_lshl_add_u32 v20, v20, 8, v20
	v_lshlrev_b32_e32 v20, 2, v20
	global_load_dword v26, v16, s[90:91] offset:1024
	global_load_dword v27, v17, s[90:91] offset:1024
	global_load_dword v28, v18, s[90:91] offset:1024
	global_load_dword v29, v19, s[90:91] offset:1024
	global_load_dword v30, v20, s[90:91] offset:1024
	v_add_u32_e32 v31, 0x20200, v11
	v_add_u32_e32 v32, 0x20200, v12
	v_add_u32_e32 v33, 0x20200, v13
	v_add_u32_e32 v34, 0x20200, v14
	v_add_u32_e32 v35, 0x20200, v15
	s_waitcnt vmcnt(0)
	v_sub_f32_e32 v21, v21, v26
	v_mul_f32_e32 v21, 0x3fb8aa3b, v21
	v_sub_f32_e32 v22, v22, v27
	v_mul_f32_e32 v22, 0x3fb8aa3b, v22
	v_sub_f32_e32 v23, v23, v28
	v_mul_f32_e32 v23, 0x3fb8aa3b, v23
	v_sub_f32_e32 v24, v24, v29
	v_mul_f32_e32 v24, 0x3fb8aa3b, v24
	v_sub_f32_e32 v25, v25, v30
	v_mul_f32_e32 v25, 0x3fb8aa3b, v25
	ds_write_b32 v31, v21
	ds_write_b32 v32, v22
	ds_write_b32 v33, v23
	ds_write_b32 v34, v24
	v_cmp_gt_u32_e32 vcc, 8, v2
	s_and_saveexec_b64 s[4:5], vcc
	ds_write_b32 v35, v25
	s_or_b64 exec, exec, s[4:5]
